# grid barrier: non-leader workgroups wait on the global generation word directly (one device-scope round trip less per barrier); per-XCD generation word no longer written
# speedup vs baseline: 1.0028x; 1.0014x over previous
; DEVI unsigned xb_ld(unsigned* p) { return __hip_atomic_load(p, __ATOMIC_RELAXED, __HIP_MEMORY_SCOPE_AGENT); }
; DEVI unsigned xb_add(unsigned* p, unsigned v) { return __hip_atomic_fetch_add(p, v, __ATOMIC_RELAXED, __HIP_MEMORY_SCOPE_AGENT); }
; #define XB_SPIN(cond, bar) do { unsigned _sp = 0; while (cond) { __builtin_amdgcn_s_sleep(1); \
;     if ((++_sp & 255u) == 0u) { if (xb_ld(&(bar)[XB_TMO])) break; if (_sp > XB_SPIN_CAP) { atomicAdd(&(bar)[XB_TMO], 1u); break; } } } } while (0)
; DEVI void xb_complete(XB& b) {
;     ...
;         for (unsigned j = 0; j < 16; ++j) { const unsigned c = xb_ld(&b.bar[XB_XCNT(j)]); sum += c; cnt += (c > 0u) ? 1u : 0u; mine = (j == b.x) ? c : mine; }
;         if (sum == G) break;
;         __builtin_amdgcn_s_sleep(1);
;         if ((++sp & 255u) == 0u) { if (xb_ld(&b.bar[XB_TMO])) break; if (sp > XB_SPIN_CAP) { atomicAdd(&b.bar[XB_TMO], 1u); break; } }
;     }
;     b.nloc = mine > 0u ? mine : 1u; b.nx = cnt > 0u ? cnt : 1u;
; }
; DEVI void gsync(XB& b) {
;     asm volatile("s_waitcnt vmcnt(0)" ::: "memory");
;     __syncthreads();
;     if (threadIdx.x == 0) {
;         unsigned* bar = b.bar;
;         __builtin_amdgcn_s_waitcnt(0);
;         if (b.nloc == 0u) xb_complete(b);
;         const unsigned nloc = b.nloc, nx = b.nx;
;         const unsigned old = xb_add(&bar[XB_XSUB(b.x)], 1u);
;         const unsigned gen = old / nloc;
;         if (old + 1u == (gen + 1u) * nloc) {
;             __builtin_amdgcn_fence(__ATOMIC_RELEASE, "agent");
;             asm volatile("s_waitcnt vmcnt(0)" ::: "memory");
;             const unsigned og = xb_add(&bar[XB_TOP], 1u);
;             const unsigned tg = og / nx;
;             if (og + 1u == (tg + 1u) * nx) xb_add(&bar[XB_TOPGEN], 1u);
;             else XB_SPIN(xb_ld(&bar[XB_TOPGEN]) == tg, bar);
;             __builtin_amdgcn_fence(__ATOMIC_ACQUIRE, "agent");
;             xb_add(&bar[XB_XGEN(b.x)], 1u);
;             asm volatile("s_waitcnt vmcnt(0)" ::: "memory");
;         } else {
;             XB_SPIN(xb_ld(&bar[XB_XGEN(b.x)]) == gen, bar);
.LBB0_46:
	s_or_b64 exec, exec, s[8:9]
	v_readlane_b32 s6, v230, 16
	s_cmp_eq_u32 s6, 0
	s_cselect_b64 vcc, -1, 0
	s_cmp_eq_u32 s6, 1
	v_cndmask_b32_e32 v19, 0, v16, vcc
	s_cselect_b64 vcc, -1, 0
	s_cmp_eq_u32 s6, 2
	v_cndmask_b32_e32 v19, v19, v3, vcc
	s_cselect_b64 vcc, -1, 0
	s_cmp_eq_u32 s6, 3
	v_cndmask_b32_e32 v19, v19, v4, vcc
	s_cselect_b64 vcc, -1, 0
	s_cmp_eq_u32 s6, 4
	v_cndmask_b32_e32 v19, v19, v5, vcc
	s_cselect_b64 vcc, -1, 0
	s_cmp_eq_u32 s6, 5
	v_cndmask_b32_e32 v19, v19, v6, vcc
	s_cselect_b64 vcc, -1, 0
	s_cmp_eq_u32 s6, 6
	v_cndmask_b32_e32 v19, v19, v7, vcc
	s_cselect_b64 vcc, -1, 0
	s_cmp_eq_u32 s6, 7
	v_cndmask_b32_e32 v19, v19, v8, vcc
	s_cselect_b64 vcc, -1, 0
	s_cmp_eq_u32 s6, 8
	v_cndmask_b32_e32 v19, v19, v10, vcc
	s_cselect_b64 vcc, -1, 0
	s_cmp_eq_u32 s6, 9
	v_cndmask_b32_e32 v19, v19, v11, vcc
	s_cselect_b64 vcc, -1, 0
	s_cmp_eq_u32 s6, 10
	v_cndmask_b32_e32 v19, v19, v12, vcc
	s_cselect_b64 vcc, -1, 0
	s_cmp_eq_u32 s6, 11
	v_cndmask_b32_e32 v19, v19, v13, vcc
	s_cselect_b64 vcc, -1, 0
	s_cmp_eq_u32 s6, 12
	v_cndmask_b32_e32 v19, v19, v14, vcc
	s_cselect_b64 vcc, -1, 0
	s_cmp_eq_u32 s6, 13
	v_cndmask_b32_e32 v19, v19, v15, vcc
	s_cselect_b64 vcc, -1, 0
	s_cmp_eq_u32 s6, 14
	v_cndmask_b32_e32 v19, v19, v1, vcc
	s_cselect_b64 vcc, -1, 0
	s_cmp_eq_u32 s6, 15
	v_cndmask_b32_e32 v19, v19, v2, vcc
	s_cselect_b64 vcc, -1, 0
	v_cndmask_b32_e32 v19, v19, v0, vcc
	v_cmp_ne_u32_e32 vcc, 0, v16
	v_max_u32_e32 v178, 1, v19
	s_waitcnt vmcnt(0)
	v_readfirstlane_b32 s6, v18
	v_cndmask_b32_e64 v16, 0, 1, vcc
	v_cmp_ne_u32_e32 vcc, 0, v3
	s_nop 1
	v_addc_co_u32_e32 v3, vcc, 0, v16, vcc
	v_cmp_ne_u32_e32 vcc, 0, v4
	s_nop 1
	v_cndmask_b32_e64 v4, 0, 1, vcc
	v_cmp_ne_u32_e32 vcc, 0, v5
	v_cvt_f32_u32_e32 v5, v178
	s_nop 0
	v_addc_co_u32_e32 v3, vcc, v3, v4, vcc
	v_cmp_ne_u32_e32 vcc, 0, v6
	s_nop 1
	v_cndmask_b32_e64 v4, 0, 1, vcc
	v_cmp_ne_u32_e32 vcc, 0, v7
	s_nop 1
	v_addc_co_u32_e32 v3, vcc, v3, v4, vcc
	v_cmp_ne_u32_e32 vcc, 0, v8
	s_nop 1
	v_cndmask_b32_e64 v4, 0, 1, vcc
	v_cmp_ne_u32_e32 vcc, 0, v10
	s_nop 1
	v_addc_co_u32_e32 v3, vcc, v3, v4, vcc
	v_cmp_ne_u32_e32 vcc, 0, v11
	s_nop 1
	v_cndmask_b32_e64 v4, 0, 1, vcc
	v_cmp_ne_u32_e32 vcc, 0, v12
	s_nop 1
	v_addc_co_u32_e32 v3, vcc, v3, v4, vcc
	v_cmp_ne_u32_e32 vcc, 0, v13
	s_nop 1
	v_cndmask_b32_e64 v4, 0, 1, vcc
	v_cmp_ne_u32_e32 vcc, 0, v14
	s_nop 1
	v_addc_co_u32_e32 v3, vcc, v3, v4, vcc
	v_cmp_ne_u32_e32 vcc, 0, v15
	s_nop 1
	v_cndmask_b32_e64 v4, 0, 1, vcc
	v_cmp_ne_u32_e32 vcc, 0, v1
	s_nop 1
	v_addc_co_u32_e32 v1, vcc, v3, v4, vcc
	v_rcp_iflag_f32_e32 v3, v5
	v_cmp_ne_u32_e32 vcc, 0, v2
	s_nop 1
	v_cndmask_b32_e64 v2, 0, 1, vcc
	v_cmp_ne_u32_e32 vcc, 0, v0
	s_nop 1
	v_addc_co_u32_e32 v0, vcc, v1, v2, vcc
	v_mul_f32_e32 v1, 0x4f7ffffe, v3
	v_cvt_u32_f32_e32 v1, v1
	v_sub_u32_e32 v3, 0, v178
	v_add_u32_e32 v2, s6, v17
	v_mul_lo_u32 v3, v3, v1
	v_mul_hi_u32 v3, v1, v3
	v_add_u32_e32 v1, v1, v3
	v_mul_hi_u32 v1, v2, v1
	v_mul_lo_u32 v3, v1, v178
	v_sub_u32_e32 v3, v2, v3
	v_add_u32_e32 v4, 1, v1
	v_cmp_ge_u32_e32 vcc, v3, v178
	v_add_u32_e32 v2, 1, v2
	s_nop 0
	v_cndmask_b32_e32 v1, v1, v4, vcc
	v_sub_u32_e32 v4, v3, v178
	v_cndmask_b32_e32 v3, v3, v4, vcc
	v_add_u32_e32 v4, 1, v1
	v_cmp_ge_u32_e32 vcc, v3, v178
	s_nop 1
	v_cndmask_b32_e32 v1, v1, v4, vcc
	v_mul_lo_u32 v3, v178, v1
	v_add_u32_e32 v3, v3, v178
	v_cmp_ne_u32_e32 vcc, v2, v3
	s_and_saveexec_b64 s[6:7], vcc
	s_xor_b64 s[6:7], exec, s[6:7]
	s_cbranch_execz .LBB0_60
	v_mov_b32_e32 v2, 0x1ef4b000
	global_load_dword v2, v2, s[90:91] offset:1280 sc1
	s_add_u32 s10, s90, 0x1ef4b500
	s_addc_u32 s11, s91, 0
	s_waitcnt vmcnt(0)
	v_cmp_eq_u32_e32 vcc, v2, v1
	s_and_saveexec_b64 s[8:9], vcc
	s_cbranch_execz .LBB0_59
	s_mov_b32 s22, 1
	s_mov_b64 s[12:13], 0
	v_mov_b32_e32 v2, 0
	s_branch .LBB0_50

; DEVI unsigned xb_ld(unsigned* p) { return __hip_atomic_load(p, __ATOMIC_RELAXED, __HIP_MEMORY_SCOPE_AGENT); }
; DEVI unsigned xb_add(unsigned* p, unsigned v) { return __hip_atomic_fetch_add(p, v, __ATOMIC_RELAXED, __HIP_MEMORY_SCOPE_AGENT); }
; #define XB_SPIN(cond, bar) do { unsigned _sp = 0; while (cond) { __builtin_amdgcn_s_sleep(1); \
;     if ((++_sp & 255u) == 0u) { if (xb_ld(&(bar)[XB_TMO])) break; if (_sp > XB_SPIN_CAP) { atomicAdd(&(bar)[XB_TMO], 1u); break; } } } } while (0)
; DEVI void gsync(XB& b) {
;     ...
;             else XB_SPIN(xb_ld(&bar[XB_TOPGEN]) == tg, bar);
;             __builtin_amdgcn_fence(__ATOMIC_ACQUIRE, "agent");
;             xb_add(&bar[XB_XGEN(b.x)], 1u);
;             asm volatile("s_waitcnt vmcnt(0)" ::: "memory");
.LBB0_77:
	s_or_b64 exec, exec, s[2:3]
	s_mov_b64 s[2:3], exec
	v_mbcnt_lo_u32_b32 v0, s2, 0
	v_mbcnt_hi_u32_b32 v0, s3, v0
	v_cmp_eq_u32_e32 vcc, 0, v0
	s_waitcnt vmcnt(0)
	buffer_inv sc1
	s_and_saveexec_b64 s[8:9], vcc
	s_cbranch_execz .LBB0_79
	s_bcnt1_i32_b64 s2, s[2:3]
	v_mov_b32_e32 v0, 0x2000
	v_mov_b32_e32 v1, s2
.LBB0_79:
	s_or_b64 exec, exec, s[8:9]
	s_waitcnt vmcnt(0)

; DEVI unsigned xb_ld(unsigned* p) { return __hip_atomic_load(p, __ATOMIC_RELAXED, __HIP_MEMORY_SCOPE_AGENT); }
; DEVI unsigned xb_add(unsigned* p, unsigned v) { return __hip_atomic_fetch_add(p, v, __ATOMIC_RELAXED, __HIP_MEMORY_SCOPE_AGENT); }
; #define XB_SPIN(cond, bar) do { unsigned _sp = 0; while (cond) { __builtin_amdgcn_s_sleep(1); \
;     if ((++_sp & 255u) == 0u) { if (xb_ld(&(bar)[XB_TMO])) break; if (_sp > XB_SPIN_CAP) { atomicAdd(&(bar)[XB_TMO], 1u); break; } } } } while (0)
; DEVI void gsync(XB& b) {
;     ...
;         const unsigned old = xb_add(&bar[XB_XSUB(b.x)], 1u);
;         const unsigned gen = old / nloc;
;         if (old + 1u == (gen + 1u) * nloc) {
;             __builtin_amdgcn_fence(__ATOMIC_RELEASE, "agent");
;             asm volatile("s_waitcnt vmcnt(0)" ::: "memory");
;             const unsigned og = xb_add(&bar[XB_TOP], 1u);
;             const unsigned tg = og / nx;
;             if (og + 1u == (tg + 1u) * nx) xb_add(&bar[XB_TOPGEN], 1u);
;             else XB_SPIN(xb_ld(&bar[XB_TOPGEN]) == tg, bar);
;             __builtin_amdgcn_fence(__ATOMIC_ACQUIRE, "agent");
;             xb_add(&bar[XB_XGEN(b.x)], 1u);
;             asm volatile("s_waitcnt vmcnt(0)" ::: "memory");
;         } else {
;             XB_SPIN(xb_ld(&bar[XB_XGEN(b.x)]) == gen, bar);
.LBB0_182:
	s_or_b64 exec, exec, s[6:7]
	v_cvt_f32_u32_e32 v2, v178
	s_waitcnt vmcnt(0)
	v_readfirstlane_b32 s4, v1
	v_rcp_iflag_f32_e32 v2, v2
	s_nop 0
	v_add_u32_e32 v0, s4, v0
	v_add_u32_e32 v4, 1, v0
	v_mul_f32_e32 v1, 0x4f7ffffe, v2
	v_cvt_u32_f32_e32 v1, v1
	v_sub_u32_e32 v2, 0, v178
	v_mul_lo_u32 v2, v2, v1
	v_mul_hi_u32 v2, v1, v2
	v_add_u32_e32 v1, v1, v2
	v_mul_hi_u32 v1, v0, v1
	v_mul_lo_u32 v2, v1, v178
	v_sub_u32_e32 v0, v0, v2
	v_add_u32_e32 v3, 1, v1
	v_cmp_ge_u32_e32 vcc, v0, v178
	v_sub_u32_e32 v2, v0, v178
	s_nop 0
	v_cndmask_b32_e32 v1, v1, v3, vcc
	v_cndmask_b32_e32 v0, v0, v2, vcc
	v_add_u32_e32 v2, 1, v1
	v_cmp_ge_u32_e32 vcc, v0, v178
	s_nop 1
	v_cndmask_b32_e32 v0, v1, v2, vcc
	v_mad_u64_u32 v[2:3], s[4:5], v178, v0, v[178:179]
	v_cmp_ne_u32_e32 vcc, v4, v2
	s_and_saveexec_b64 s[4:5], vcc
	s_xor_b64 s[4:5], exec, s[4:5]
	s_cbranch_execz .LBB0_196
	v_mov_b32_e32 v1, 0x1ef4b000
	global_load_dword v1, v1, s[90:91] offset:1280 sc1
	s_add_u32 s10, s90, 0x1ef4b500
	s_addc_u32 s11, s91, 0
	s_waitcnt vmcnt(0)
	v_cmp_eq_u32_e32 vcc, v1, v0
	s_and_saveexec_b64 s[6:7], vcc
	s_cbranch_execz .LBB0_195
	s_add_u32 s8, s90, 0x1ef48200
	s_addc_u32 s9, s91, 0
	s_mov_b32 s16, 1
	s_mov_b64 s[12:13], 0
	v_mov_b32_e32 v1, 0
	s_branch .LBB0_186

; DEVI unsigned xb_ld(unsigned* p) { return __hip_atomic_load(p, __ATOMIC_RELAXED, __HIP_MEMORY_SCOPE_AGENT); }
; DEVI unsigned xb_add(unsigned* p, unsigned v) { return __hip_atomic_fetch_add(p, v, __ATOMIC_RELAXED, __HIP_MEMORY_SCOPE_AGENT); }
; #define XB_SPIN(cond, bar) do { unsigned _sp = 0; while (cond) { __builtin_amdgcn_s_sleep(1); \
;     if ((++_sp & 255u) == 0u) { if (xb_ld(&(bar)[XB_TMO])) break; if (_sp > XB_SPIN_CAP) { atomicAdd(&(bar)[XB_TMO], 1u); break; } } } } while (0)
; DEVI void gsync(XB& b) {
;     ...
;             __builtin_amdgcn_fence(__ATOMIC_RELEASE, "agent");
;             asm volatile("s_waitcnt vmcnt(0)" ::: "memory");
;             const unsigned og = xb_add(&bar[XB_TOP], 1u);
;             const unsigned tg = og / nx;
;             if (og + 1u == (tg + 1u) * nx) xb_add(&bar[XB_TOPGEN], 1u);
;             else XB_SPIN(xb_ld(&bar[XB_TOPGEN]) == tg, bar);
;             __builtin_amdgcn_fence(__ATOMIC_ACQUIRE, "agent");
;             xb_add(&bar[XB_XGEN(b.x)], 1u);
;             asm volatile("s_waitcnt vmcnt(0)" ::: "memory");
.LBB0_213:
	s_or_b64 exec, exec, s[6:7]
	s_mov_b64 s[6:7], exec
	v_mbcnt_lo_u32_b32 v0, s6, 0
	v_mbcnt_hi_u32_b32 v0, s7, v0
	v_cmp_eq_u32_e32 vcc, 0, v0
	s_waitcnt vmcnt(0)
	buffer_inv sc1
	s_and_saveexec_b64 s[8:9], vcc
	s_cbranch_execz .LBB0_215
	s_bcnt1_i32_b64 s6, s[6:7]
	v_mov_b32_e32 v0, 0x2000
	v_mov_b32_e32 v1, s6
.LBB0_215:
	s_or_b64 exec, exec, s[8:9]
	s_waitcnt vmcnt(0)

; DEVI unsigned xb_ld(unsigned* p) { return __hip_atomic_load(p, __ATOMIC_RELAXED, __HIP_MEMORY_SCOPE_AGENT); }
; DEVI unsigned xb_add(unsigned* p, unsigned v) { return __hip_atomic_fetch_add(p, v, __ATOMIC_RELAXED, __HIP_MEMORY_SCOPE_AGENT); }
; #define XB_SPIN(cond, bar) do { unsigned _sp = 0; while (cond) { __builtin_amdgcn_s_sleep(1); \
;     if ((++_sp & 255u) == 0u) { if (xb_ld(&(bar)[XB_TMO])) break; if (_sp > XB_SPIN_CAP) { atomicAdd(&(bar)[XB_TMO], 1u); break; } } } } while (0)
; DEVI void gsync(XB& b) {
;     ...
;             __builtin_amdgcn_fence(__ATOMIC_RELEASE, "agent");
;             asm volatile("s_waitcnt vmcnt(0)" ::: "memory");
;             const unsigned og = xb_add(&bar[XB_TOP], 1u);
;             const unsigned tg = og / nx;
;             if (og + 1u == (tg + 1u) * nx) xb_add(&bar[XB_TOPGEN], 1u);
;             else XB_SPIN(xb_ld(&bar[XB_TOPGEN]) == tg, bar);
;             __builtin_amdgcn_fence(__ATOMIC_ACQUIRE, "agent");
;             xb_add(&bar[XB_XGEN(b.x)], 1u);
;             asm volatile("s_waitcnt vmcnt(0)" ::: "memory");
.LBB0_461:
	s_or_b64 exec, exec, s[6:7]
	s_mov_b64 s[6:7], exec
	v_mbcnt_lo_u32_b32 v0, s6, 0
	v_mbcnt_hi_u32_b32 v0, s7, v0
	v_cmp_eq_u32_e32 vcc, 0, v0
	s_waitcnt vmcnt(0)
	buffer_inv sc1
	s_and_saveexec_b64 s[8:9], vcc
	s_cbranch_execz .LBB0_463
	s_bcnt1_i32_b64 s6, s[6:7]
	v_mov_b32_e32 v0, 0x2000
	v_mov_b32_e32 v1, s6
.LBB0_463:
	s_or_b64 exec, exec, s[8:9]
	s_waitcnt vmcnt(0)

; DEVI unsigned xb_ld(unsigned* p) { return __hip_atomic_load(p, __ATOMIC_RELAXED, __HIP_MEMORY_SCOPE_AGENT); }
; DEVI unsigned xb_add(unsigned* p, unsigned v) { return __hip_atomic_fetch_add(p, v, __ATOMIC_RELAXED, __HIP_MEMORY_SCOPE_AGENT); }
; #define XB_SPIN(cond, bar) do { unsigned _sp = 0; while (cond) { __builtin_amdgcn_s_sleep(1); \
;     if ((++_sp & 255u) == 0u) { if (xb_ld(&(bar)[XB_TMO])) break; if (_sp > XB_SPIN_CAP) { atomicAdd(&(bar)[XB_TMO], 1u); break; } } } } while (0)
; DEVI void gsync(XB& b) {
;     ...
;         const unsigned old = xb_add(&bar[XB_XSUB(b.x)], 1u);
;         const unsigned gen = old / nloc;
;         if (old + 1u == (gen + 1u) * nloc) {
;             __builtin_amdgcn_fence(__ATOMIC_RELEASE, "agent");
;             asm volatile("s_waitcnt vmcnt(0)" ::: "memory");
;             const unsigned og = xb_add(&bar[XB_TOP], 1u);
;             const unsigned tg = og / nx;
;             if (og + 1u == (tg + 1u) * nx) xb_add(&bar[XB_TOPGEN], 1u);
;             else XB_SPIN(xb_ld(&bar[XB_TOPGEN]) == tg, bar);
;             __builtin_amdgcn_fence(__ATOMIC_ACQUIRE, "agent");
;             xb_add(&bar[XB_XGEN(b.x)], 1u);
;             asm volatile("s_waitcnt vmcnt(0)" ::: "memory");
;         } else {
;             XB_SPIN(xb_ld(&bar[XB_XGEN(b.x)]) == gen, bar);
.LBB0_616:
	s_or_b64 exec, exec, s[6:7]
	v_cvt_f32_u32_e32 v2, v178
	s_waitcnt vmcnt(0)
	v_readfirstlane_b32 s4, v1
	v_rcp_iflag_f32_e32 v2, v2
	s_nop 0
	v_add_u32_e32 v0, s4, v0
	v_add_u32_e32 v4, 1, v0
	v_mul_f32_e32 v1, 0x4f7ffffe, v2
	v_cvt_u32_f32_e32 v1, v1
	v_sub_u32_e32 v2, 0, v178
	v_mul_lo_u32 v2, v2, v1
	v_mul_hi_u32 v2, v1, v2
	v_add_u32_e32 v1, v1, v2
	v_mul_hi_u32 v1, v0, v1
	v_mul_lo_u32 v2, v1, v178
	v_sub_u32_e32 v0, v0, v2
	v_add_u32_e32 v3, 1, v1
	v_cmp_ge_u32_e32 vcc, v0, v178
	v_sub_u32_e32 v2, v0, v178
	s_nop 0
	v_cndmask_b32_e32 v1, v1, v3, vcc
	v_cndmask_b32_e32 v0, v0, v2, vcc
	v_add_u32_e32 v2, 1, v1
	v_cmp_ge_u32_e32 vcc, v0, v178
	s_nop 1
	v_cndmask_b32_e32 v0, v1, v2, vcc
	v_mad_u64_u32 v[2:3], s[4:5], v178, v0, v[178:179]
	v_cmp_ne_u32_e32 vcc, v4, v2
	s_and_saveexec_b64 s[4:5], vcc
	s_xor_b64 s[4:5], exec, s[4:5]
	s_cbranch_execz .LBB0_630
	v_mov_b32_e32 v1, 0x1ef4b000
	global_load_dword v1, v1, s[90:91] offset:1280 sc1
	s_add_u32 s10, s90, 0x1ef4b500
	s_addc_u32 s11, s91, 0
	s_waitcnt vmcnt(0)
	v_cmp_eq_u32_e32 vcc, v1, v0
	s_and_saveexec_b64 s[6:7], vcc
	s_cbranch_execz .LBB0_629
	s_add_u32 s8, s90, 0x1ef48200
	s_addc_u32 s9, s91, 0
	s_mov_b32 s22, 1
	s_mov_b64 s[12:13], 0
	v_mov_b32_e32 v1, 0
	s_branch .LBB0_620

; DEVI unsigned xb_ld(unsigned* p) { return __hip_atomic_load(p, __ATOMIC_RELAXED, __HIP_MEMORY_SCOPE_AGENT); }
; DEVI unsigned xb_add(unsigned* p, unsigned v) { return __hip_atomic_fetch_add(p, v, __ATOMIC_RELAXED, __HIP_MEMORY_SCOPE_AGENT); }
; #define XB_SPIN(cond, bar) do { unsigned _sp = 0; while (cond) { __builtin_amdgcn_s_sleep(1); \
;     if ((++_sp & 255u) == 0u) { if (xb_ld(&(bar)[XB_TMO])) break; if (_sp > XB_SPIN_CAP) { atomicAdd(&(bar)[XB_TMO], 1u); break; } } } } while (0)
; DEVI void gsync(XB& b) {
;     ...
;             __builtin_amdgcn_fence(__ATOMIC_RELEASE, "agent");
;             asm volatile("s_waitcnt vmcnt(0)" ::: "memory");
;             const unsigned og = xb_add(&bar[XB_TOP], 1u);
;             const unsigned tg = og / nx;
;             if (og + 1u == (tg + 1u) * nx) xb_add(&bar[XB_TOPGEN], 1u);
;             else XB_SPIN(xb_ld(&bar[XB_TOPGEN]) == tg, bar);
;             __builtin_amdgcn_fence(__ATOMIC_ACQUIRE, "agent");
;             xb_add(&bar[XB_XGEN(b.x)], 1u);
;             asm volatile("s_waitcnt vmcnt(0)" ::: "memory");
.LBB0_647:
	s_or_b64 exec, exec, s[6:7]
	s_mov_b64 s[6:7], exec
	v_mbcnt_lo_u32_b32 v0, s6, 0
	v_mbcnt_hi_u32_b32 v0, s7, v0
	v_cmp_eq_u32_e32 vcc, 0, v0
	s_waitcnt vmcnt(0)
	buffer_inv sc1
	s_and_saveexec_b64 s[8:9], vcc
	s_cbranch_execz .LBB0_649
	s_bcnt1_i32_b64 s6, s[6:7]
	v_mov_b32_e32 v0, 0x2000
	v_mov_b32_e32 v1, s6
.LBB0_649:
	s_or_b64 exec, exec, s[8:9]
	s_waitcnt vmcnt(0)

; DEVI unsigned xb_ld(unsigned* p) { return __hip_atomic_load(p, __ATOMIC_RELAXED, __HIP_MEMORY_SCOPE_AGENT); }
; DEVI unsigned xb_add(unsigned* p, unsigned v) { return __hip_atomic_fetch_add(p, v, __ATOMIC_RELAXED, __HIP_MEMORY_SCOPE_AGENT); }
; #define XB_SPIN(cond, bar) do { unsigned _sp = 0; while (cond) { __builtin_amdgcn_s_sleep(1); \
;     if ((++_sp & 255u) == 0u) { if (xb_ld(&(bar)[XB_TMO])) break; if (_sp > XB_SPIN_CAP) { atomicAdd(&(bar)[XB_TMO], 1u); break; } } } } while (0)
; DEVI void gsync(XB& b) {
;     ...
;             __builtin_amdgcn_fence(__ATOMIC_RELEASE, "agent");
;             asm volatile("s_waitcnt vmcnt(0)" ::: "memory");
;             const unsigned og = xb_add(&bar[XB_TOP], 1u);
;             const unsigned tg = og / nx;
;             if (og + 1u == (tg + 1u) * nx) xb_add(&bar[XB_TOPGEN], 1u);
;             else XB_SPIN(xb_ld(&bar[XB_TOPGEN]) == tg, bar);
;             __builtin_amdgcn_fence(__ATOMIC_ACQUIRE, "agent");
;             xb_add(&bar[XB_XGEN(b.x)], 1u);
;             asm volatile("s_waitcnt vmcnt(0)" ::: "memory");
.LBB0_703:
	s_or_b64 exec, exec, s[6:7]
	s_mov_b64 s[6:7], exec
	v_mbcnt_lo_u32_b32 v0, s6, 0
	v_mbcnt_hi_u32_b32 v0, s7, v0
	v_cmp_eq_u32_e32 vcc, 0, v0
	s_waitcnt vmcnt(0)
	buffer_inv sc1
	s_and_saveexec_b64 s[8:9], vcc
	s_cbranch_execz .LBB0_705
	s_bcnt1_i32_b64 s6, s[6:7]
	v_mov_b32_e32 v0, 0x2000
	v_mov_b32_e32 v1, s6
.LBB0_705:
	s_or_b64 exec, exec, s[8:9]
	s_waitcnt vmcnt(0)

; DEVI unsigned xb_ld(unsigned* p) { return __hip_atomic_load(p, __ATOMIC_RELAXED, __HIP_MEMORY_SCOPE_AGENT); }
; DEVI unsigned xb_add(unsigned* p, unsigned v) { return __hip_atomic_fetch_add(p, v, __ATOMIC_RELAXED, __HIP_MEMORY_SCOPE_AGENT); }
; #define XB_SPIN(cond, bar) do { unsigned _sp = 0; while (cond) { __builtin_amdgcn_s_sleep(1); \
;     if ((++_sp & 255u) == 0u) { if (xb_ld(&(bar)[XB_TMO])) break; if (_sp > XB_SPIN_CAP) { atomicAdd(&(bar)[XB_TMO], 1u); break; } } } } while (0)
; DEVI void gsync(XB& b) {
;     ...
;             __builtin_amdgcn_fence(__ATOMIC_RELEASE, "agent");
;             asm volatile("s_waitcnt vmcnt(0)" ::: "memory");
;             const unsigned og = xb_add(&bar[XB_TOP], 1u);
;             const unsigned tg = og / nx;
;             if (og + 1u == (tg + 1u) * nx) xb_add(&bar[XB_TOPGEN], 1u);
;             else XB_SPIN(xb_ld(&bar[XB_TOPGEN]) == tg, bar);
;             __builtin_amdgcn_fence(__ATOMIC_ACQUIRE, "agent");
;             xb_add(&bar[XB_XGEN(b.x)], 1u);
;             asm volatile("s_waitcnt vmcnt(0)" ::: "memory");
.LBB0_1184:
	s_or_b64 exec, exec, s[6:7]
	s_mov_b64 s[6:7], exec
	v_mbcnt_lo_u32_b32 v0, s6, 0
	v_mbcnt_hi_u32_b32 v0, s7, v0
	v_cmp_eq_u32_e32 vcc, 0, v0
	s_waitcnt vmcnt(0)
	buffer_inv sc1
	s_and_saveexec_b64 s[8:9], vcc
	s_cbranch_execz .LBB0_1186
	s_bcnt1_i32_b64 s6, s[6:7]
	v_mov_b32_e32 v0, 0x2000
	v_mov_b32_e32 v1, s6
.LBB0_1186:
	s_or_b64 exec, exec, s[8:9]
	s_waitcnt vmcnt(0)

; DEVI unsigned xb_ld(unsigned* p) { return __hip_atomic_load(p, __ATOMIC_RELAXED, __HIP_MEMORY_SCOPE_AGENT); }
; DEVI unsigned xb_add(unsigned* p, unsigned v) { return __hip_atomic_fetch_add(p, v, __ATOMIC_RELAXED, __HIP_MEMORY_SCOPE_AGENT); }
; #define XB_SPIN(cond, bar) do { unsigned _sp = 0; while (cond) { __builtin_amdgcn_s_sleep(1); \
;     if ((++_sp & 255u) == 0u) { if (xb_ld(&(bar)[XB_TMO])) break; if (_sp > XB_SPIN_CAP) { atomicAdd(&(bar)[XB_TMO], 1u); break; } } } } while (0)
; DEVI void gsync(XB& b) {
;     ...
;             __builtin_amdgcn_fence(__ATOMIC_RELEASE, "agent");
;             asm volatile("s_waitcnt vmcnt(0)" ::: "memory");
;             const unsigned og = xb_add(&bar[XB_TOP], 1u);
;             const unsigned tg = og / nx;
;             if (og + 1u == (tg + 1u) * nx) xb_add(&bar[XB_TOPGEN], 1u);
;             else XB_SPIN(xb_ld(&bar[XB_TOPGEN]) == tg, bar);
;             __builtin_amdgcn_fence(__ATOMIC_ACQUIRE, "agent");
;             xb_add(&bar[XB_XGEN(b.x)], 1u);
;             asm volatile("s_waitcnt vmcnt(0)" ::: "memory");
.LBB0_1246:
	s_or_b64 exec, exec, s[6:7]
	s_mov_b64 s[6:7], exec
	v_mbcnt_lo_u32_b32 v0, s6, 0
	v_mbcnt_hi_u32_b32 v0, s7, v0
	v_cmp_eq_u32_e32 vcc, 0, v0
	s_waitcnt vmcnt(0)
	buffer_inv sc1
	s_and_saveexec_b64 s[8:9], vcc
	s_cbranch_execz .LBB0_1248
	s_bcnt1_i32_b64 s6, s[6:7]
	v_mov_b32_e32 v0, 0x2000
	v_mov_b32_e32 v1, s6
.LBB0_1248:
	s_or_b64 exec, exec, s[8:9]
	s_waitcnt vmcnt(0)

; DEVI unsigned xb_ld(unsigned* p) { return __hip_atomic_load(p, __ATOMIC_RELAXED, __HIP_MEMORY_SCOPE_AGENT); }
; DEVI unsigned xb_add(unsigned* p, unsigned v) { return __hip_atomic_fetch_add(p, v, __ATOMIC_RELAXED, __HIP_MEMORY_SCOPE_AGENT); }
; #define XB_SPIN(cond, bar) do { unsigned _sp = 0; while (cond) { __builtin_amdgcn_s_sleep(1); \
;     if ((++_sp & 255u) == 0u) { if (xb_ld(&(bar)[XB_TMO])) break; if (_sp > XB_SPIN_CAP) { atomicAdd(&(bar)[XB_TMO], 1u); break; } } } } while (0)
; DEVI void gsync(XB& b) {
;     ...
;             __builtin_amdgcn_fence(__ATOMIC_RELEASE, "agent");
;             asm volatile("s_waitcnt vmcnt(0)" ::: "memory");
;             const unsigned og = xb_add(&bar[XB_TOP], 1u);
;             const unsigned tg = og / nx;
;             if (og + 1u == (tg + 1u) * nx) xb_add(&bar[XB_TOPGEN], 1u);
;             else XB_SPIN(xb_ld(&bar[XB_TOPGEN]) == tg, bar);
;             __builtin_amdgcn_fence(__ATOMIC_ACQUIRE, "agent");
;             xb_add(&bar[XB_XGEN(b.x)], 1u);
;             asm volatile("s_waitcnt vmcnt(0)" ::: "memory");
.LBB0_1326:
	s_or_b64 exec, exec, s[6:7]
	s_mov_b64 s[6:7], exec
	v_mbcnt_lo_u32_b32 v0, s6, 0
	v_mbcnt_hi_u32_b32 v0, s7, v0
	v_cmp_eq_u32_e32 vcc, 0, v0
	s_waitcnt vmcnt(0)
	buffer_inv sc1
	s_and_saveexec_b64 s[8:9], vcc
	s_cbranch_execz .LBB0_1328
	s_bcnt1_i32_b64 s6, s[6:7]
	v_mov_b32_e32 v0, 0x2000
	v_mov_b32_e32 v1, s6
.LBB0_1328:
	s_or_b64 exec, exec, s[8:9]
	s_waitcnt vmcnt(0)

; DEVI unsigned xb_ld(unsigned* p) { return __hip_atomic_load(p, __ATOMIC_RELAXED, __HIP_MEMORY_SCOPE_AGENT); }
; DEVI unsigned xb_add(unsigned* p, unsigned v) { return __hip_atomic_fetch_add(p, v, __ATOMIC_RELAXED, __HIP_MEMORY_SCOPE_AGENT); }
; #define XB_SPIN(cond, bar) do { unsigned _sp = 0; while (cond) { __builtin_amdgcn_s_sleep(1); \
;     if ((++_sp & 255u) == 0u) { if (xb_ld(&(bar)[XB_TMO])) break; if (_sp > XB_SPIN_CAP) { atomicAdd(&(bar)[XB_TMO], 1u); break; } } } } while (0)
; DEVI void gsync(XB& b) {
;     ...
;         const unsigned old = xb_add(&bar[XB_XSUB(b.x)], 1u);
;         const unsigned gen = old / nloc;
;         if (old + 1u == (gen + 1u) * nloc) {
;             __builtin_amdgcn_fence(__ATOMIC_RELEASE, "agent");
;             asm volatile("s_waitcnt vmcnt(0)" ::: "memory");
;             const unsigned og = xb_add(&bar[XB_TOP], 1u);
;             const unsigned tg = og / nx;
;             if (og + 1u == (tg + 1u) * nx) xb_add(&bar[XB_TOPGEN], 1u);
;             else XB_SPIN(xb_ld(&bar[XB_TOPGEN]) == tg, bar);
;             __builtin_amdgcn_fence(__ATOMIC_ACQUIRE, "agent");
;             xb_add(&bar[XB_XGEN(b.x)], 1u);
;             asm volatile("s_waitcnt vmcnt(0)" ::: "memory");
;         } else {
;             XB_SPIN(xb_ld(&bar[XB_XGEN(b.x)]) == gen, bar);
.LBB0_1392:
	s_or_b64 exec, exec, s[8:9]
	v_cvt_f32_u32_e32 v2, v178
	s_waitcnt vmcnt(0)
	v_readfirstlane_b32 s6, v1
	v_rcp_iflag_f32_e32 v2, v2
	s_nop 0
	v_add_u32_e32 v0, s6, v0
	v_add_u32_e32 v4, 1, v0
	v_mul_f32_e32 v1, 0x4f7ffffe, v2
	v_cvt_u32_f32_e32 v1, v1
	v_sub_u32_e32 v2, 0, v178
	v_mul_lo_u32 v2, v2, v1
	v_mul_hi_u32 v2, v1, v2
	v_add_u32_e32 v1, v1, v2
	v_mul_hi_u32 v1, v0, v1
	v_mul_lo_u32 v2, v1, v178
	v_sub_u32_e32 v0, v0, v2
	v_add_u32_e32 v3, 1, v1
	v_cmp_ge_u32_e32 vcc, v0, v178
	v_sub_u32_e32 v2, v0, v178
	s_nop 0
	v_cndmask_b32_e32 v1, v1, v3, vcc
	v_cndmask_b32_e32 v0, v0, v2, vcc
	v_add_u32_e32 v2, 1, v1
	v_cmp_ge_u32_e32 vcc, v0, v178
	s_nop 1
	v_cndmask_b32_e32 v0, v1, v2, vcc
	v_mad_u64_u32 v[2:3], s[6:7], v178, v0, v[178:179]
	v_cmp_ne_u32_e32 vcc, v4, v2
	s_and_saveexec_b64 s[6:7], vcc
	s_xor_b64 s[6:7], exec, s[6:7]
	s_cbranch_execz .LBB0_1406
	v_mov_b32_e32 v1, 0x1ef4b000
	global_load_dword v1, v1, s[90:91] offset:1280 sc1
	s_add_u32 s12, s90, 0x1ef4b500
	s_addc_u32 s13, s91, 0
	s_waitcnt vmcnt(0)
	v_cmp_eq_u32_e32 vcc, v1, v0
	s_and_saveexec_b64 s[8:9], vcc
	s_cbranch_execz .LBB0_1405
	s_add_u32 s10, s90, 0x1ef48200
	s_addc_u32 s11, s91, 0
	s_mov_b32 s24, 1
	s_mov_b64 s[14:15], 0
	v_mov_b32_e32 v1, 0
	s_branch .LBB0_1396

; DEVI unsigned xb_ld(unsigned* p) { return __hip_atomic_load(p, __ATOMIC_RELAXED, __HIP_MEMORY_SCOPE_AGENT); }
; DEVI unsigned xb_add(unsigned* p, unsigned v) { return __hip_atomic_fetch_add(p, v, __ATOMIC_RELAXED, __HIP_MEMORY_SCOPE_AGENT); }
; #define XB_SPIN(cond, bar) do { unsigned _sp = 0; while (cond) { __builtin_amdgcn_s_sleep(1); \
;     if ((++_sp & 255u) == 0u) { if (xb_ld(&(bar)[XB_TMO])) break; if (_sp > XB_SPIN_CAP) { atomicAdd(&(bar)[XB_TMO], 1u); break; } } } } while (0)
; DEVI void gsync(XB& b) {
;     ...
;             __builtin_amdgcn_fence(__ATOMIC_RELEASE, "agent");
;             asm volatile("s_waitcnt vmcnt(0)" ::: "memory");
;             const unsigned og = xb_add(&bar[XB_TOP], 1u);
;             const unsigned tg = og / nx;
;             if (og + 1u == (tg + 1u) * nx) xb_add(&bar[XB_TOPGEN], 1u);
;             else XB_SPIN(xb_ld(&bar[XB_TOPGEN]) == tg, bar);
;             __builtin_amdgcn_fence(__ATOMIC_ACQUIRE, "agent");
;             xb_add(&bar[XB_XGEN(b.x)], 1u);
;             asm volatile("s_waitcnt vmcnt(0)" ::: "memory");
.LBB0_1423:
	s_or_b64 exec, exec, s[8:9]
	s_mov_b64 s[8:9], exec
	v_mbcnt_lo_u32_b32 v0, s8, 0
	v_mbcnt_hi_u32_b32 v0, s9, v0
	v_cmp_eq_u32_e32 vcc, 0, v0
	s_waitcnt vmcnt(0)
	buffer_inv sc1
	s_and_saveexec_b64 s[10:11], vcc
	s_cbranch_execz .LBB0_1425
	s_bcnt1_i32_b64 s8, s[8:9]
	v_mov_b32_e32 v0, 0x2000
	v_mov_b32_e32 v1, s8
.LBB0_1425:
	s_or_b64 exec, exec, s[10:11]
	s_waitcnt vmcnt(0)

; DEVI unsigned xb_ld(unsigned* p) { return __hip_atomic_load(p, __ATOMIC_RELAXED, __HIP_MEMORY_SCOPE_AGENT); }
; DEVI unsigned xb_add(unsigned* p, unsigned v) { return __hip_atomic_fetch_add(p, v, __ATOMIC_RELAXED, __HIP_MEMORY_SCOPE_AGENT); }
; #define XB_SPIN(cond, bar) do { unsigned _sp = 0; while (cond) { __builtin_amdgcn_s_sleep(1); \
;     if ((++_sp & 255u) == 0u) { if (xb_ld(&(bar)[XB_TMO])) break; if (_sp > XB_SPIN_CAP) { atomicAdd(&(bar)[XB_TMO], 1u); break; } } } } while (0)
; DEVI void gsync(XB& b) {
;     ...
;             __builtin_amdgcn_fence(__ATOMIC_RELEASE, "agent");
;             asm volatile("s_waitcnt vmcnt(0)" ::: "memory");
;             const unsigned og = xb_add(&bar[XB_TOP], 1u);
;             const unsigned tg = og / nx;
;             if (og + 1u == (tg + 1u) * nx) xb_add(&bar[XB_TOPGEN], 1u);
;             else XB_SPIN(xb_ld(&bar[XB_TOPGEN]) == tg, bar);
;             __builtin_amdgcn_fence(__ATOMIC_ACQUIRE, "agent");
;             xb_add(&bar[XB_XGEN(b.x)], 1u);
;             asm volatile("s_waitcnt vmcnt(0)" ::: "memory");
.LBB0_1493:
	s_or_b64 exec, exec, s[6:7]
	s_mov_b64 s[6:7], exec
	v_mbcnt_lo_u32_b32 v0, s6, 0
	v_mbcnt_hi_u32_b32 v0, s7, v0
	v_cmp_eq_u32_e32 vcc, 0, v0
	s_waitcnt vmcnt(0)
	buffer_inv sc1
	s_and_saveexec_b64 s[8:9], vcc
	s_cbranch_execz .LBB0_1495
	s_bcnt1_i32_b64 s6, s[6:7]
	v_mov_b32_e32 v0, 0x2000
	v_mov_b32_e32 v1, s6
.LBB0_1495:
	s_or_b64 exec, exec, s[8:9]
	s_waitcnt vmcnt(0)

; DEVI unsigned xb_ld(unsigned* p) { return __hip_atomic_load(p, __ATOMIC_RELAXED, __HIP_MEMORY_SCOPE_AGENT); }
; DEVI unsigned xb_add(unsigned* p, unsigned v) { return __hip_atomic_fetch_add(p, v, __ATOMIC_RELAXED, __HIP_MEMORY_SCOPE_AGENT); }
; #define XB_SPIN(cond, bar) do { unsigned _sp = 0; while (cond) { __builtin_amdgcn_s_sleep(1); \
;     if ((++_sp & 255u) == 0u) { if (xb_ld(&(bar)[XB_TMO])) break; if (_sp > XB_SPIN_CAP) { atomicAdd(&(bar)[XB_TMO], 1u); break; } } } } while (0)
; DEVI void gsync(XB& b) {
;     ...
;             __builtin_amdgcn_fence(__ATOMIC_RELEASE, "agent");
;             asm volatile("s_waitcnt vmcnt(0)" ::: "memory");
;             const unsigned og = xb_add(&bar[XB_TOP], 1u);
;             const unsigned tg = og / nx;
;             if (og + 1u == (tg + 1u) * nx) xb_add(&bar[XB_TOPGEN], 1u);
;             else XB_SPIN(xb_ld(&bar[XB_TOPGEN]) == tg, bar);
;             __builtin_amdgcn_fence(__ATOMIC_ACQUIRE, "agent");
;             xb_add(&bar[XB_XGEN(b.x)], 1u);
;             asm volatile("s_waitcnt vmcnt(0)" ::: "memory");
.LBB0_1555:
	s_or_b64 exec, exec, s[4:5]
	s_mov_b64 s[4:5], exec
	v_mbcnt_lo_u32_b32 v0, s4, 0
	v_mbcnt_hi_u32_b32 v0, s5, v0
	v_cmp_eq_u32_e32 vcc, 0, v0
	s_waitcnt vmcnt(0)
	buffer_inv sc1
	s_and_saveexec_b64 s[6:7], vcc
	s_cbranch_execz .LBB0_1557
	s_bcnt1_i32_b64 s4, s[4:5]
	v_mov_b32_e32 v0, 0x2000
	v_mov_b32_e32 v1, s4
.LBB0_1557:
	s_or_b64 exec, exec, s[6:7]
	s_waitcnt vmcnt(0)
